# attention softmax: lazy running-max update only (rescale when the tile max exceeds the running max by 8 in log2 units)
# speedup vs baseline: 1.0112x; 1.0008x over previous
; __device__ __forceinline__ void attn_tile(const LAS bf16_t* kl, unsigned vaddr, int kt, const bf16x8 (&qf)[8], f32x16 (&o)[4], float& mrun, float& lrun, int r, int h, int rr, int p, int hd, size_t qtok,
;                                           bf16_t* __restrict__ OP, float* __restrict__ LSE) {
;     ...
;     float mx = fmaxf(fmaxf(s[0], s[1]), fmaxf(s[2], s[3]));
; #pragma unroll
;     for (int i = 4; i < 16; i += 4) mx = fmaxf(mx, fmaxf(fmaxf(s[i], s[i + 1]), fmaxf(s[i + 2], s[i + 3])));
;     { const auto pr = __builtin_amdgcn_permlane32_swap(__float_as_uint(mx), __float_as_uint(mx), false, false); mx = fmaxf(__uint_as_float(pr[0]), __uint_as_float(pr[1])); }
;     const float mnew = fmaxf(mrun, mx * scl);
;     const float alpha = __builtin_amdgcn_exp2f(mrun - mnew);
;     float rs = 0.f;
; #pragma unroll
;     for (int i = 0; i < 16; ++i) { s[i] = __builtin_amdgcn_exp2f(__builtin_fmaf(s[i], scl, -mnew)); rs += s[i]; }
;     { const auto pr = __builtin_amdgcn_permlane32_swap(__float_as_uint(rs), __float_as_uint(rs), false, false); rs = __uint_as_float(pr[0]) + __uint_as_float(pr[1]); }
;     lrun = lrun * alpha + rs; mrun = mnew;
;     if (__builtin_amdgcn_readfirstlane(__any(alpha != 1.0f) ? 1 : 0)) {
; #pragma unroll
;         for (int dt = 0; dt < 4; ++dt)
; #pragma unroll
;             for (int i = 0; i < 16; ++i) o[dt][i] *= alpha;
;     }
.LBB0_526:
	v_max_f32_e32 v1, v108, v108
	v_max_f32_e32 v14, v109, v109
	v_max_f32_e32 v1, v14, v1
	v_max_f32_e32 v14, v106, v106
	v_max_f32_e32 v15, v107, v107
	v_max_f32_e32 v14, v15, v14
	v_max_f32_e32 v15, v103, v103
	v_max_f32_e32 v80, v101, v101
	v_max_f32_e32 v15, v80, v15
	v_max3_f32 v15, v105, v99, v15
	v_max3_f32 v1, v1, v14, v15
	v_max_f32_e32 v14, v98, v98
	v_max_f32_e32 v15, v100, v100
	v_max_f32_e32 v14, v15, v14
	v_max_f32_e32 v15, v94, v94
	v_max_f32_e32 v80, v95, v95
	v_max_f32_e32 v15, v80, v15
	v_max3_f32 v14, v104, v102, v14
	v_max3_f32 v15, v97, v96, v15
	v_max3_f32 v1, v1, v14, v15
	v_mov_b32_e32 v14, v1
	s_nop 1
	v_permlane32_swap_b32_e32 v1, v14
	v_max_f32_e32 v14, v14, v14
	v_max_f32_e32 v1, v1, v1
	v_max_f32_e32 v1, v1, v14
	v_mul_f32_e32 v1, 0x3e0293ee, v1
	v_max_f32_e32 v14, v187, v187
	v_add_f32_e32 v80, 0x41000000, v14
	v_cmp_gt_f32_e32 vcc, v1, v80
	s_nop 1
	v_cndmask_b32_e32 v1, v14, v1, vcc
	v_fma_f32 v14, v109, s74, -v1
	v_exp_f32_e32 v89, v14
	v_fma_f32 v80, v108, s74, -v1
	v_exp_f32_e32 v90, v80
	v_fma_f32 v80, v107, s74, -v1
	v_exp_f32_e32 v91, v80
	v_fma_f32 v80, v106, s74, -v1
	v_exp_f32_e32 v92, v80
	v_fma_f32 v80, v105, s74, -v1
	v_add_f32_e32 v15, 0, v89
	v_exp_f32_e32 v93, v80
	v_fma_f32 v80, v99, s74, -v1
	v_add_f32_e32 v15, v90, v15
	v_exp_f32_e32 v99, v80
	v_fma_f32 v80, v101, s74, -v1
	v_add_f32_e32 v15, v91, v15
	v_exp_f32_e32 v101, v80
	v_fma_f32 v80, v103, s74, -v1
	v_add_f32_e32 v15, v92, v15
	v_exp_f32_e32 v103, v80
	v_fma_f32 v80, v104, s74, -v1
	v_add_f32_e32 v15, v93, v15
	v_exp_f32_e32 v81, v80
	v_fma_f32 v80, v102, s74, -v1
	v_add_f32_e32 v15, v99, v15
	v_exp_f32_e32 v82, v80
	v_fma_f32 v80, v100, s74, -v1
	v_add_f32_e32 v15, v101, v15
	v_exp_f32_e32 v83, v80
	v_fma_f32 v80, v98, s74, -v1
	v_sub_f32_e32 v14, v187, v1
	v_add_f32_e32 v15, v103, v15
	v_exp_f32_e32 v84, v80
	v_fma_f32 v80, v97, s74, -v1
	v_add_f32_e32 v15, v81, v15
	v_exp_f32_e32 v85, v80
	v_fma_f32 v80, v96, s74, -v1
	v_exp_f32_e32 v14, v14
	v_add_f32_e32 v15, v82, v15
	v_exp_f32_e32 v86, v80
	v_fma_f32 v80, v95, s74, -v1
	v_add_f32_e32 v15, v83, v15
	v_exp_f32_e32 v87, v80
	v_fma_f32 v80, v94, s74, -v1
	v_add_f32_e32 v15, v84, v15
	v_exp_f32_e32 v88, v80
	v_add_f32_e32 v15, v85, v15
	v_cmp_neq_f32_e32 vcc, 1.0, v14
	v_add_f32_e32 v15, v86, v15
	s_cmp_lg_u64 vcc, 0
	v_add_f32_e32 v15, v87, v15
	s_cselect_b64 s[38:39], -1, 0
	v_add_f32_e32 v15, v88, v15
	v_cndmask_b32_e64 v94, 0, 1, s[38:39]
	v_mov_b32_e32 v80, v15
	v_readfirstlane_b32 s33, v94
	s_bitcmp0_b32 s33, 0
	v_permlane32_swap_b32_e32 v15, v80
	s_cbranch_scc1 .LBB0_528
	v_pk_mul_f32 v[78:79], v[78:79], v[14:15] op_sel_hi:[1,0]
	v_pk_mul_f32 v[76:77], v[76:77], v[14:15] op_sel_hi:[1,0]
	v_pk_mul_f32 v[74:75], v[74:75], v[14:15] op_sel_hi:[1,0]
	v_pk_mul_f32 v[72:73], v[72:73], v[14:15] op_sel_hi:[1,0]
	v_pk_mul_f32 v[70:71], v[70:71], v[14:15] op_sel_hi:[1,0]
	v_pk_mul_f32 v[68:69], v[68:69], v[14:15] op_sel_hi:[1,0]
	v_pk_mul_f32 v[66:67], v[66:67], v[14:15] op_sel_hi:[1,0]
	v_pk_mul_f32 v[64:65], v[64:65], v[14:15] op_sel_hi:[1,0]
	v_pk_mul_f32 v[62:63], v[62:63], v[14:15] op_sel_hi:[1,0]
	v_pk_mul_f32 v[60:61], v[60:61], v[14:15] op_sel_hi:[1,0]
	v_pk_mul_f32 v[58:59], v[58:59], v[14:15] op_sel_hi:[1,0]
	v_pk_mul_f32 v[56:57], v[56:57], v[14:15] op_sel_hi:[1,0]
	v_pk_mul_f32 v[54:55], v[54:55], v[14:15] op_sel_hi:[1,0]
	v_pk_mul_f32 v[52:53], v[52:53], v[14:15] op_sel_hi:[1,0]
	v_pk_mul_f32 v[50:51], v[50:51], v[14:15] op_sel_hi:[1,0]
	v_pk_mul_f32 v[48:49], v[48:49], v[14:15] op_sel_hi:[1,0]
	v_pk_mul_f32 v[46:47], v[46:47], v[14:15] op_sel_hi:[1,0]
	v_pk_mul_f32 v[44:45], v[44:45], v[14:15] op_sel_hi:[1,0]
	v_pk_mul_f32 v[42:43], v[42:43], v[14:15] op_sel_hi:[1,0]
	v_pk_mul_f32 v[40:41], v[40:41], v[14:15] op_sel_hi:[1,0]
	v_pk_mul_f32 v[38:39], v[38:39], v[14:15] op_sel_hi:[1,0]
	v_pk_mul_f32 v[36:37], v[36:37], v[14:15] op_sel_hi:[1,0]
	v_pk_mul_f32 v[34:35], v[34:35], v[14:15] op_sel_hi:[1,0]
	v_pk_mul_f32 v[32:33], v[32:33], v[14:15] op_sel_hi:[1,0]
	v_pk_mul_f32 v[30:31], v[30:31], v[14:15] op_sel_hi:[1,0]
	v_pk_mul_f32 v[28:29], v[28:29], v[14:15] op_sel_hi:[1,0]
	v_pk_mul_f32 v[26:27], v[26:27], v[14:15] op_sel_hi:[1,0]
	v_pk_mul_f32 v[24:25], v[24:25], v[14:15] op_sel_hi:[1,0]
	v_pk_mul_f32 v[22:23], v[22:23], v[14:15] op_sel_hi:[1,0]
	v_pk_mul_f32 v[20:21], v[20:21], v[14:15] op_sel_hi:[1,0]
	v_pk_mul_f32 v[18:19], v[18:19], v[14:15] op_sel_hi:[1,0]
	v_pk_mul_f32 v[16:17], v[16:17], v[14:15] op_sel_hi:[1,0]

; __device__ __forceinline__ void attn_tile(const LAS bf16_t* kl, unsigned vaddr, int kt, const bf16x8 (&qf)[8], f32x16 (&o)[4], float& mrun, float& lrun, int r, int h, int rr, int p, int hd, size_t qtok,
;                                           bf16_t* __restrict__ OP, float* __restrict__ LSE) {
;     ...
;     float mx = fmaxf(fmaxf(s[0], s[1]), fmaxf(s[2], s[3]));
; #pragma unroll
;     for (int i = 4; i < 16; i += 4) mx = fmaxf(mx, fmaxf(fmaxf(s[i], s[i + 1]), fmaxf(s[i + 2], s[i + 3])));
;     { const auto pr = __builtin_amdgcn_permlane32_swap(__float_as_uint(mx), __float_as_uint(mx), false, false); mx = fmaxf(__uint_as_float(pr[0]), __uint_as_float(pr[1])); }
;     const float mnew = fmaxf(mrun, mx * scl);
;     const float alpha = __builtin_amdgcn_exp2f(mrun - mnew);
;     float rs = 0.f;
; #pragma unroll
;     for (int i = 0; i < 16; ++i) { s[i] = __builtin_amdgcn_exp2f(__builtin_fmaf(s[i], scl, -mnew)); rs += s[i]; }
;     { const auto pr = __builtin_amdgcn_permlane32_swap(__float_as_uint(rs), __float_as_uint(rs), false, false); rs = __uint_as_float(pr[0]) + __uint_as_float(pr[1]); }
;     lrun = lrun * alpha + rs; mrun = mnew;
;     if (__builtin_amdgcn_readfirstlane(__any(alpha != 1.0f) ? 1 : 0)) {
; #pragma unroll
;         for (int dt = 0; dt < 4; ++dt)
; #pragma unroll
;             for (int i = 0; i < 16; ++i) o[dt][i] *= alpha;
;     }
.LBB0_549:
	v_max_f32_e32 v1, v108, v108
	v_max_f32_e32 v14, v109, v109
	v_max_f32_e32 v1, v14, v1
	v_max_f32_e32 v14, v106, v106
	v_max_f32_e32 v15, v107, v107
	v_max_f32_e32 v14, v15, v14
	v_max_f32_e32 v15, v103, v103
	v_max_f32_e32 v80, v101, v101
	v_max_f32_e32 v15, v80, v15
	v_max3_f32 v15, v105, v99, v15
	v_max3_f32 v1, v1, v14, v15
	v_max_f32_e32 v14, v98, v98
	v_max_f32_e32 v15, v100, v100
	v_max_f32_e32 v14, v15, v14
	v_max_f32_e32 v15, v94, v94
	v_max_f32_e32 v80, v95, v95
	v_max_f32_e32 v15, v80, v15
	v_max3_f32 v14, v104, v102, v14
	v_max3_f32 v15, v97, v96, v15
	v_max3_f32 v1, v1, v14, v15
	v_mov_b32_e32 v14, v1
	s_nop 1
	v_permlane32_swap_b32_e32 v1, v14
	v_max_f32_e32 v14, v14, v14
	v_max_f32_e32 v1, v1, v1
	v_max_f32_e32 v1, v1, v14
	v_mul_f32_e32 v1, 0x3e0293ee, v1
	v_max_f32_e32 v14, v187, v187
	v_add_f32_e32 v80, 0x41000000, v14
	v_cmp_gt_f32_e32 vcc, v1, v80
	s_nop 1
	v_cndmask_b32_e32 v1, v14, v1, vcc
	v_fma_f32 v14, v109, s74, -v1
	v_exp_f32_e32 v89, v14
	v_fma_f32 v80, v108, s74, -v1
	v_exp_f32_e32 v90, v80
	v_fma_f32 v80, v107, s74, -v1
	v_exp_f32_e32 v91, v80
	v_fma_f32 v80, v106, s74, -v1
	v_exp_f32_e32 v92, v80
	v_fma_f32 v80, v105, s74, -v1
	v_add_f32_e32 v15, 0, v89
	v_exp_f32_e32 v93, v80
	v_fma_f32 v80, v99, s74, -v1
	v_add_f32_e32 v15, v90, v15
	v_exp_f32_e32 v99, v80
	v_fma_f32 v80, v101, s74, -v1
	v_add_f32_e32 v15, v91, v15
	v_exp_f32_e32 v101, v80
	v_fma_f32 v80, v103, s74, -v1
	v_add_f32_e32 v15, v92, v15
	v_exp_f32_e32 v103, v80
	v_fma_f32 v80, v104, s74, -v1
	v_add_f32_e32 v15, v93, v15
	v_exp_f32_e32 v81, v80
	v_fma_f32 v80, v102, s74, -v1
	v_add_f32_e32 v15, v99, v15
	v_exp_f32_e32 v82, v80
	v_fma_f32 v80, v100, s74, -v1
	v_add_f32_e32 v15, v101, v15
	v_exp_f32_e32 v83, v80
	v_fma_f32 v80, v98, s74, -v1
	v_sub_f32_e32 v14, v187, v1
	v_add_f32_e32 v15, v103, v15
	v_exp_f32_e32 v84, v80
	v_fma_f32 v80, v97, s74, -v1
	v_add_f32_e32 v15, v81, v15
	v_exp_f32_e32 v85, v80
	v_fma_f32 v80, v96, s74, -v1
	v_exp_f32_e32 v14, v14
	v_add_f32_e32 v15, v82, v15
	v_exp_f32_e32 v86, v80
	v_fma_f32 v80, v95, s74, -v1
	v_add_f32_e32 v15, v83, v15
	v_exp_f32_e32 v87, v80
	v_fma_f32 v80, v94, s74, -v1
	v_add_f32_e32 v15, v84, v15
	v_exp_f32_e32 v88, v80
	v_add_f32_e32 v15, v85, v15
	v_cmp_neq_f32_e32 vcc, 1.0, v14
	v_add_f32_e32 v15, v86, v15
	s_cmp_lg_u64 vcc, 0
	v_add_f32_e32 v15, v87, v15
	s_cselect_b64 s[36:37], -1, 0
	v_add_f32_e32 v15, v88, v15
	v_cndmask_b32_e64 v94, 0, 1, s[36:37]
	v_mov_b32_e32 v80, v15
	v_readfirstlane_b32 s33, v94
	s_bitcmp0_b32 s33, 0
	v_permlane32_swap_b32_e32 v15, v80
	s_cbranch_scc1 .LBB0_551
	v_pk_mul_f32 v[78:79], v[78:79], v[14:15] op_sel_hi:[1,0]
	v_pk_mul_f32 v[76:77], v[76:77], v[14:15] op_sel_hi:[1,0]
	v_pk_mul_f32 v[74:75], v[74:75], v[14:15] op_sel_hi:[1,0]
	v_pk_mul_f32 v[72:73], v[72:73], v[14:15] op_sel_hi:[1,0]
	v_pk_mul_f32 v[70:71], v[70:71], v[14:15] op_sel_hi:[1,0]
	v_pk_mul_f32 v[68:69], v[68:69], v[14:15] op_sel_hi:[1,0]
	v_pk_mul_f32 v[66:67], v[66:67], v[14:15] op_sel_hi:[1,0]
	v_pk_mul_f32 v[64:65], v[64:65], v[14:15] op_sel_hi:[1,0]
	v_pk_mul_f32 v[62:63], v[62:63], v[14:15] op_sel_hi:[1,0]
	v_pk_mul_f32 v[60:61], v[60:61], v[14:15] op_sel_hi:[1,0]
	v_pk_mul_f32 v[58:59], v[58:59], v[14:15] op_sel_hi:[1,0]
	v_pk_mul_f32 v[56:57], v[56:57], v[14:15] op_sel_hi:[1,0]
	v_pk_mul_f32 v[54:55], v[54:55], v[14:15] op_sel_hi:[1,0]
	v_pk_mul_f32 v[52:53], v[52:53], v[14:15] op_sel_hi:[1,0]
	v_pk_mul_f32 v[50:51], v[50:51], v[14:15] op_sel_hi:[1,0]
	v_pk_mul_f32 v[48:49], v[48:49], v[14:15] op_sel_hi:[1,0]
	v_pk_mul_f32 v[46:47], v[46:47], v[14:15] op_sel_hi:[1,0]
	v_pk_mul_f32 v[44:45], v[44:45], v[14:15] op_sel_hi:[1,0]
	v_pk_mul_f32 v[42:43], v[42:43], v[14:15] op_sel_hi:[1,0]
	v_pk_mul_f32 v[40:41], v[40:41], v[14:15] op_sel_hi:[1,0]
	v_pk_mul_f32 v[38:39], v[38:39], v[14:15] op_sel_hi:[1,0]
	v_pk_mul_f32 v[36:37], v[36:37], v[14:15] op_sel_hi:[1,0]
	v_pk_mul_f32 v[34:35], v[34:35], v[14:15] op_sel_hi:[1,0]
	v_pk_mul_f32 v[32:33], v[32:33], v[14:15] op_sel_hi:[1,0]
	v_pk_mul_f32 v[30:31], v[30:31], v[14:15] op_sel_hi:[1,0]
	v_pk_mul_f32 v[28:29], v[28:29], v[14:15] op_sel_hi:[1,0]
	v_pk_mul_f32 v[26:27], v[26:27], v[14:15] op_sel_hi:[1,0]
	v_pk_mul_f32 v[24:25], v[24:25], v[14:15] op_sel_hi:[1,0]
	v_pk_mul_f32 v[22:23], v[22:23], v[14:15] op_sel_hi:[1,0]
	v_pk_mul_f32 v[20:21], v[20:21], v[14:15] op_sel_hi:[1,0]
	v_pk_mul_f32 v[18:19], v[18:19], v[14:15] op_sel_hi:[1,0]
	v_pk_mul_f32 v[16:17], v[16:17], v[14:15] op_sel_hi:[1,0]

; __device__ __forceinline__ void attn_tile(const LAS bf16_t* kl, unsigned vaddr, int kt, const bf16x8 (&qf)[8], f32x16 (&o)[4], float& mrun, float& lrun, int r, int h, int rr, int p, int hd, size_t qtok,
;                                           bf16_t* __restrict__ OP, float* __restrict__ LSE) {
;     ...
;     float mx = fmaxf(fmaxf(s[0], s[1]), fmaxf(s[2], s[3]));
; #pragma unroll
;     for (int i = 4; i < 16; i += 4) mx = fmaxf(mx, fmaxf(fmaxf(s[i], s[i + 1]), fmaxf(s[i + 2], s[i + 3])));
;     { const auto pr = __builtin_amdgcn_permlane32_swap(__float_as_uint(mx), __float_as_uint(mx), false, false); mx = fmaxf(__uint_as_float(pr[0]), __uint_as_float(pr[1])); }
;     const float mnew = fmaxf(mrun, mx * scl);
;     const float alpha = __builtin_amdgcn_exp2f(mrun - mnew);
;     float rs = 0.f;
; #pragma unroll
;     for (int i = 0; i < 16; ++i) { s[i] = __builtin_amdgcn_exp2f(__builtin_fmaf(s[i], scl, -mnew)); rs += s[i]; }
;     { const auto pr = __builtin_amdgcn_permlane32_swap(__float_as_uint(rs), __float_as_uint(rs), false, false); rs = __uint_as_float(pr[0]) + __uint_as_float(pr[1]); }
;     lrun = lrun * alpha + rs; mrun = mnew;
;     if (__builtin_amdgcn_readfirstlane(__any(alpha != 1.0f) ? 1 : 0)) {
; #pragma unroll
;         for (int dt = 0; dt < 4; ++dt)
; #pragma unroll
;             for (int i = 0; i < 16; ++i) o[dt][i] *= alpha;
;     }
.LBB0_587:
	v_max_f32_e32 v1, v108, v108
	v_max_f32_e32 v14, v109, v109
	v_max_f32_e32 v1, v14, v1
	v_max_f32_e32 v14, v106, v106
	v_max_f32_e32 v15, v107, v107
	v_max_f32_e32 v14, v15, v14
	v_max_f32_e32 v15, v103, v103
	v_max_f32_e32 v80, v101, v101
	v_max_f32_e32 v15, v80, v15
	v_max3_f32 v15, v105, v99, v15
	v_max3_f32 v1, v1, v14, v15
	v_max_f32_e32 v14, v98, v98
	v_max_f32_e32 v15, v100, v100
	v_max_f32_e32 v14, v15, v14
	v_max_f32_e32 v15, v94, v94
	v_max_f32_e32 v80, v95, v95
	v_max_f32_e32 v15, v80, v15
	v_max3_f32 v14, v104, v102, v14
	v_max3_f32 v15, v97, v96, v15
	v_max3_f32 v1, v1, v14, v15
	v_mov_b32_e32 v14, v1
	s_nop 1
	v_permlane32_swap_b32_e32 v1, v14
	v_max_f32_e32 v14, v14, v14
	v_max_f32_e32 v1, v1, v1
	v_max_f32_e32 v1, v1, v14
	v_mul_f32_e32 v1, 0x3e0293ee, v1
	v_max_f32_e32 v14, v183, v183
	v_add_f32_e32 v80, 0x41000000, v14
	v_cmp_gt_f32_e32 vcc, v1, v80
	s_nop 1
	v_cndmask_b32_e32 v1, v14, v1, vcc
	v_fma_f32 v14, v109, s43, -v1
	v_exp_f32_e32 v89, v14
	v_fma_f32 v80, v108, s43, -v1
	v_exp_f32_e32 v90, v80
	v_fma_f32 v80, v107, s43, -v1
	v_exp_f32_e32 v91, v80
	v_fma_f32 v80, v106, s43, -v1
	v_exp_f32_e32 v92, v80
	v_fma_f32 v80, v105, s43, -v1
	v_add_f32_e32 v15, 0, v89
	v_exp_f32_e32 v93, v80
	v_fma_f32 v80, v99, s43, -v1
	v_add_f32_e32 v15, v90, v15
	v_exp_f32_e32 v99, v80
	v_fma_f32 v80, v101, s43, -v1
	v_add_f32_e32 v15, v91, v15
	v_exp_f32_e32 v101, v80
	v_fma_f32 v80, v103, s43, -v1
	v_add_f32_e32 v15, v92, v15
	v_exp_f32_e32 v103, v80
	v_fma_f32 v80, v104, s43, -v1
	v_add_f32_e32 v15, v93, v15
	v_exp_f32_e32 v81, v80
	v_fma_f32 v80, v102, s43, -v1
	v_add_f32_e32 v15, v99, v15
	v_exp_f32_e32 v82, v80
	v_fma_f32 v80, v100, s43, -v1
	v_add_f32_e32 v15, v101, v15
	v_exp_f32_e32 v83, v80
	v_fma_f32 v80, v98, s43, -v1
	v_sub_f32_e32 v14, v183, v1
	v_add_f32_e32 v15, v103, v15
	v_exp_f32_e32 v84, v80
	v_fma_f32 v80, v97, s43, -v1
	v_add_f32_e32 v15, v81, v15
	v_exp_f32_e32 v85, v80
	v_fma_f32 v80, v96, s43, -v1
	v_exp_f32_e32 v14, v14
	v_add_f32_e32 v15, v82, v15
	v_exp_f32_e32 v86, v80
	v_fma_f32 v80, v95, s43, -v1
	v_add_f32_e32 v15, v83, v15
	v_exp_f32_e32 v87, v80
	v_fma_f32 v80, v94, s43, -v1
	v_add_f32_e32 v15, v84, v15
	v_exp_f32_e32 v88, v80
	v_add_f32_e32 v15, v85, v15
	v_cmp_neq_f32_e32 vcc, 1.0, v14
	v_add_f32_e32 v15, v86, v15
	s_cmp_lg_u64 vcc, 0
	v_add_f32_e32 v15, v87, v15
	s_cselect_b64 s[36:37], -1, 0
	v_add_f32_e32 v15, v88, v15
	v_cndmask_b32_e64 v94, 0, 1, s[36:37]
	v_mov_b32_e32 v80, v15
	v_readfirstlane_b32 s33, v94
	s_bitcmp0_b32 s33, 0
	v_permlane32_swap_b32_e32 v15, v80
	s_cbranch_scc1 .LBB0_589
	v_pk_mul_f32 v[78:79], v[78:79], v[14:15] op_sel_hi:[1,0]
	v_pk_mul_f32 v[76:77], v[76:77], v[14:15] op_sel_hi:[1,0]
	v_pk_mul_f32 v[74:75], v[74:75], v[14:15] op_sel_hi:[1,0]
	v_pk_mul_f32 v[72:73], v[72:73], v[14:15] op_sel_hi:[1,0]
	v_pk_mul_f32 v[70:71], v[70:71], v[14:15] op_sel_hi:[1,0]
	v_pk_mul_f32 v[68:69], v[68:69], v[14:15] op_sel_hi:[1,0]
	v_pk_mul_f32 v[66:67], v[66:67], v[14:15] op_sel_hi:[1,0]
	v_pk_mul_f32 v[64:65], v[64:65], v[14:15] op_sel_hi:[1,0]
	v_pk_mul_f32 v[62:63], v[62:63], v[14:15] op_sel_hi:[1,0]
	v_pk_mul_f32 v[60:61], v[60:61], v[14:15] op_sel_hi:[1,0]
	v_pk_mul_f32 v[58:59], v[58:59], v[14:15] op_sel_hi:[1,0]
	v_pk_mul_f32 v[56:57], v[56:57], v[14:15] op_sel_hi:[1,0]
	v_pk_mul_f32 v[54:55], v[54:55], v[14:15] op_sel_hi:[1,0]
	v_pk_mul_f32 v[52:53], v[52:53], v[14:15] op_sel_hi:[1,0]
	v_pk_mul_f32 v[50:51], v[50:51], v[14:15] op_sel_hi:[1,0]
	v_pk_mul_f32 v[48:49], v[48:49], v[14:15] op_sel_hi:[1,0]
	v_pk_mul_f32 v[46:47], v[46:47], v[14:15] op_sel_hi:[1,0]
	v_pk_mul_f32 v[44:45], v[44:45], v[14:15] op_sel_hi:[1,0]
	v_pk_mul_f32 v[42:43], v[42:43], v[14:15] op_sel_hi:[1,0]
	v_pk_mul_f32 v[40:41], v[40:41], v[14:15] op_sel_hi:[1,0]
	v_pk_mul_f32 v[38:39], v[38:39], v[14:15] op_sel_hi:[1,0]
	v_pk_mul_f32 v[36:37], v[36:37], v[14:15] op_sel_hi:[1,0]
	v_pk_mul_f32 v[34:35], v[34:35], v[14:15] op_sel_hi:[1,0]
	v_pk_mul_f32 v[32:33], v[32:33], v[14:15] op_sel_hi:[1,0]
	v_pk_mul_f32 v[30:31], v[30:31], v[14:15] op_sel_hi:[1,0]
	v_pk_mul_f32 v[28:29], v[28:29], v[14:15] op_sel_hi:[1,0]
	v_pk_mul_f32 v[26:27], v[26:27], v[14:15] op_sel_hi:[1,0]
	v_pk_mul_f32 v[24:25], v[24:25], v[14:15] op_sel_hi:[1,0]
	v_pk_mul_f32 v[22:23], v[22:23], v[14:15] op_sel_hi:[1,0]
	v_pk_mul_f32 v[20:21], v[20:21], v[14:15] op_sel_hi:[1,0]
	v_pk_mul_f32 v[18:19], v[18:19], v[14:15] op_sel_hi:[1,0]
	v_pk_mul_f32 v[16:17], v[16:17], v[14:15] op_sel_hi:[1,0]

; __device__ __forceinline__ void attn_tile(const LAS bf16_t* kl, unsigned vaddr, int kt, const bf16x8 (&qf)[8], f32x16 (&o)[4], float& mrun, float& lrun, int r, int h, int rr, int p, int hd, size_t qtok,
;                                           bf16_t* __restrict__ OP, float* __restrict__ LSE) {
;     ...
;     float mx = fmaxf(fmaxf(s[0], s[1]), fmaxf(s[2], s[3]));
; #pragma unroll
;     for (int i = 4; i < 16; i += 4) mx = fmaxf(mx, fmaxf(fmaxf(s[i], s[i + 1]), fmaxf(s[i + 2], s[i + 3])));
;     { const auto pr = __builtin_amdgcn_permlane32_swap(__float_as_uint(mx), __float_as_uint(mx), false, false); mx = fmaxf(__uint_as_float(pr[0]), __uint_as_float(pr[1])); }
;     const float mnew = fmaxf(mrun, mx * scl);
;     const float alpha = __builtin_amdgcn_exp2f(mrun - mnew);
;     float rs = 0.f;
; #pragma unroll
;     for (int i = 0; i < 16; ++i) { s[i] = __builtin_amdgcn_exp2f(__builtin_fmaf(s[i], scl, -mnew)); rs += s[i]; }
;     { const auto pr = __builtin_amdgcn_permlane32_swap(__float_as_uint(rs), __float_as_uint(rs), false, false); rs = __uint_as_float(pr[0]) + __uint_as_float(pr[1]); }
;     lrun = lrun * alpha + rs; mrun = mnew;
;     if (__builtin_amdgcn_readfirstlane(__any(alpha != 1.0f) ? 1 : 0)) {
; #pragma unroll
;         for (int dt = 0; dt < 4; ++dt)
; #pragma unroll
;             for (int i = 0; i < 16; ++i) o[dt][i] *= alpha;
;     }
.LBB0_609:
	v_max_f32_e32 v1, v108, v108
	v_max_f32_e32 v14, v109, v109
	v_max_f32_e32 v1, v14, v1
	v_max_f32_e32 v14, v106, v106
	v_max_f32_e32 v15, v107, v107
	v_max_f32_e32 v14, v15, v14
	v_max_f32_e32 v15, v103, v103
	v_max_f32_e32 v80, v101, v101
	v_max_f32_e32 v15, v80, v15
	v_max3_f32 v15, v105, v99, v15
	v_max3_f32 v1, v1, v14, v15
	v_max_f32_e32 v14, v98, v98
	v_max_f32_e32 v15, v100, v100
	v_max_f32_e32 v14, v15, v14
	v_max_f32_e32 v15, v94, v94
	v_max_f32_e32 v80, v95, v95
	v_max_f32_e32 v15, v80, v15
	v_max3_f32 v14, v104, v102, v14
	v_max3_f32 v15, v97, v96, v15
	v_max3_f32 v1, v1, v14, v15
	v_mov_b32_e32 v14, v1
	s_nop 1
	v_permlane32_swap_b32_e32 v1, v14
	v_max_f32_e32 v14, v14, v14
	v_max_f32_e32 v1, v1, v1
	v_max_f32_e32 v1, v1, v14
	v_mul_f32_e32 v1, 0x3e0293ee, v1
	v_max_f32_e32 v14, v183, v183
	v_add_f32_e32 v80, 0x41000000, v14
	v_cmp_gt_f32_e32 vcc, v1, v80
	s_nop 1
	v_cndmask_b32_e32 v1, v14, v1, vcc
	v_fma_f32 v14, v109, s43, -v1
	v_exp_f32_e32 v89, v14
	v_fma_f32 v80, v108, s43, -v1
	v_exp_f32_e32 v90, v80
	v_fma_f32 v80, v107, s43, -v1
	v_exp_f32_e32 v91, v80
	v_fma_f32 v80, v106, s43, -v1
	v_exp_f32_e32 v92, v80
	v_fma_f32 v80, v105, s43, -v1
	v_add_f32_e32 v15, 0, v89
	v_exp_f32_e32 v93, v80
	v_fma_f32 v80, v99, s43, -v1
	v_add_f32_e32 v15, v90, v15
	v_exp_f32_e32 v99, v80
	v_fma_f32 v80, v101, s43, -v1
	v_add_f32_e32 v15, v91, v15
	v_exp_f32_e32 v101, v80
	v_fma_f32 v80, v103, s43, -v1
	v_add_f32_e32 v15, v92, v15
	v_exp_f32_e32 v103, v80
	v_fma_f32 v80, v104, s43, -v1
	v_add_f32_e32 v15, v93, v15
	v_exp_f32_e32 v81, v80
	v_fma_f32 v80, v102, s43, -v1
	v_add_f32_e32 v15, v99, v15
	v_exp_f32_e32 v82, v80
	v_fma_f32 v80, v100, s43, -v1
	v_add_f32_e32 v15, v101, v15
	v_exp_f32_e32 v83, v80
	v_fma_f32 v80, v98, s43, -v1
	v_sub_f32_e32 v14, v183, v1
	v_add_f32_e32 v15, v103, v15
	v_exp_f32_e32 v84, v80
	v_fma_f32 v80, v97, s43, -v1
	v_add_f32_e32 v15, v81, v15
	v_exp_f32_e32 v85, v80
	v_fma_f32 v80, v96, s43, -v1
	v_exp_f32_e32 v14, v14
	v_add_f32_e32 v15, v82, v15
	v_exp_f32_e32 v86, v80
	v_fma_f32 v80, v95, s43, -v1
	v_add_f32_e32 v15, v83, v15
	v_exp_f32_e32 v87, v80
	v_fma_f32 v80, v94, s43, -v1
	v_add_f32_e32 v15, v84, v15
	v_exp_f32_e32 v88, v80
	v_add_f32_e32 v15, v85, v15
	v_cmp_neq_f32_e32 vcc, 1.0, v14
	v_add_f32_e32 v15, v86, v15
	s_cmp_lg_u64 vcc, 0
	v_add_f32_e32 v15, v87, v15
	s_cselect_b64 s[38:39], -1, 0
	v_add_f32_e32 v15, v88, v15
	v_cndmask_b32_e64 v94, 0, 1, s[38:39]
	v_mov_b32_e32 v80, v15
	v_readfirstlane_b32 s33, v94
	s_bitcmp0_b32 s33, 0
	v_permlane32_swap_b32_e32 v15, v80
	s_cbranch_scc1 .LBB0_611
	v_pk_mul_f32 v[78:79], v[78:79], v[14:15] op_sel_hi:[1,0]
	v_pk_mul_f32 v[76:77], v[76:77], v[14:15] op_sel_hi:[1,0]
	v_pk_mul_f32 v[74:75], v[74:75], v[14:15] op_sel_hi:[1,0]
	v_pk_mul_f32 v[72:73], v[72:73], v[14:15] op_sel_hi:[1,0]
	v_pk_mul_f32 v[70:71], v[70:71], v[14:15] op_sel_hi:[1,0]
	v_pk_mul_f32 v[68:69], v[68:69], v[14:15] op_sel_hi:[1,0]
	v_pk_mul_f32 v[66:67], v[66:67], v[14:15] op_sel_hi:[1,0]
	v_pk_mul_f32 v[64:65], v[64:65], v[14:15] op_sel_hi:[1,0]
	v_pk_mul_f32 v[62:63], v[62:63], v[14:15] op_sel_hi:[1,0]
	v_pk_mul_f32 v[60:61], v[60:61], v[14:15] op_sel_hi:[1,0]
	v_pk_mul_f32 v[58:59], v[58:59], v[14:15] op_sel_hi:[1,0]
	v_pk_mul_f32 v[56:57], v[56:57], v[14:15] op_sel_hi:[1,0]
	v_pk_mul_f32 v[54:55], v[54:55], v[14:15] op_sel_hi:[1,0]
	v_pk_mul_f32 v[52:53], v[52:53], v[14:15] op_sel_hi:[1,0]
	v_pk_mul_f32 v[50:51], v[50:51], v[14:15] op_sel_hi:[1,0]
	v_pk_mul_f32 v[48:49], v[48:49], v[14:15] op_sel_hi:[1,0]
	v_pk_mul_f32 v[46:47], v[46:47], v[14:15] op_sel_hi:[1,0]
	v_pk_mul_f32 v[44:45], v[44:45], v[14:15] op_sel_hi:[1,0]
	v_pk_mul_f32 v[42:43], v[42:43], v[14:15] op_sel_hi:[1,0]
	v_pk_mul_f32 v[40:41], v[40:41], v[14:15] op_sel_hi:[1,0]
	v_pk_mul_f32 v[38:39], v[38:39], v[14:15] op_sel_hi:[1,0]
	v_pk_mul_f32 v[36:37], v[36:37], v[14:15] op_sel_hi:[1,0]
	v_pk_mul_f32 v[34:35], v[34:35], v[14:15] op_sel_hi:[1,0]
	v_pk_mul_f32 v[32:33], v[32:33], v[14:15] op_sel_hi:[1,0]
	v_pk_mul_f32 v[30:31], v[30:31], v[14:15] op_sel_hi:[1,0]
	v_pk_mul_f32 v[28:29], v[28:29], v[14:15] op_sel_hi:[1,0]
	v_pk_mul_f32 v[26:27], v[26:27], v[14:15] op_sel_hi:[1,0]
	v_pk_mul_f32 v[24:25], v[24:25], v[14:15] op_sel_hi:[1,0]
	v_pk_mul_f32 v[22:23], v[22:23], v[14:15] op_sel_hi:[1,0]
	v_pk_mul_f32 v[20:21], v[20:21], v[14:15] op_sel_hi:[1,0]
	v_pk_mul_f32 v[18:19], v[18:19], v[14:15] op_sel_hi:[1,0]
	v_pk_mul_f32 v[16:17], v[16:17], v[14:15] op_sel_hi:[1,0]
